# forget-gate cumulative sums moved from the end of P2 (6 CUs, after the token-shift pass) into P3's slack on the same CUs after their decay tile and prefix pass
# baseline (speedup 1.0000x reference)
; __device__ __forceinline__ void phase_shift_cum(const Args& A, int gtid, int NGT, int gw, int lane) {
;     ...
;     const float* FL = (const float*)(ws + WS_FL); const float* b_f = A.in[14]; float* CUM = (float*)(ws + WS_CUM);
;     if (gw < BATCH * NH) {
;         const int b = gw / NH, h = gw % NH; const float bf = b_f[h];
;         const float* src = FL + ((size_t)b * T + lane * 64) * 256 + h; float zv[64];
; #pragma unroll
;         for (int i = 0; i < 64; ++i) zv[i] = src[(size_t)i * 256];
.LBB0_311:
	s_or_b64 exec, exec, s[4:5]
	s_ashr_i32 s0, s0, 6
	s_lshl_b32 s1, s1, 3
	s_add_i32 s4, s1, s0
	s_cmp_gt_i32 s57, 3
	s_cselect_b32 s5, 0, 48
	s_cmp_lt_i32 s4, s5
	s_cbranch_scc0 .LBB0_313
	s_mul_hi_i32 s0, s4, 0x2aaaaaab
	s_lshr_b32 s1, s0, 31
	s_ashr_i32 s0, s0, 2
	s_add_i32 s0, s0, s1
	s_load_dwordx16 s[8:23], s[62:63], 0x40
	s_mul_i32 s1, s0, 24
	s_sub_i32 s6, s4, s1
	s_ashr_i32 s7, s6, 31
	s_lshl_b64 s[6:7], s[6:7], 2
	s_waitcnt lgkmcnt(0)
	s_add_u32 s8, s20, s6
	s_addc_u32 s9, s21, s7
	s_ashr_i32 s1, s0, 31
	s_lshl_b64 s[0:1], s[0:1], 22
	v_and_b32_e32 v2, 63, v14
	s_add_u32 s0, s34, s0
	v_mov_b32_e32 v1, 0
	s_addc_u32 s1, s35, s1
	v_lshlrev_b32_e32 v0, 16, v2
	v_lshl_add_u64 v[4:5], s[0:1], 0, v[0:1]
	global_load_dword v3, v1, s[8:9]
	v_lshl_add_u64 v[4:5], v[4:5], 0, s[6:7]
	s_mov_b64 s[0:1], 0x18200000
	v_lshl_add_u64 v[6:7], v[4:5], 0, s[0:1]
	s_mov_b32 s0, 0x18201000
	v_add_co_u32_e32 v8, vcc, s0, v4
	s_mov_b32 s0, 0x18202000
	s_nop 0
	v_addc_co_u32_e32 v9, vcc, 0, v5, vcc
	v_add_co_u32_e32 v10, vcc, s0, v4
	s_mov_b32 s0, 0x18203000
	s_nop 0
	v_addc_co_u32_e32 v11, vcc, 0, v5, vcc
	v_add_co_u32_e32 v12, vcc, s0, v4
	s_mov_b32 s0, 0x18204000
	s_nop 0
	v_addc_co_u32_e32 v13, vcc, 0, v5, vcc
	global_load_dword v0, v[8:9], off offset:-4096
	global_load_dword v18, v[8:9], off
	global_load_dword v22, v[8:9], off offset:1024
	global_load_dword v23, v[8:9], off offset:2048
	global_load_dword v27, v[8:9], off offset:3072
	global_load_dword v29, v[12:13], off offset:-4096
	global_load_dword v32, v[12:13], off
	global_load_dword v35, v[12:13], off offset:1024
	v_add_co_u32_e32 v8, vcc, s0, v4
	s_mov_b32 s0, 0x18205000
	s_nop 0
	v_addc_co_u32_e32 v9, vcc, 0, v5, vcc
	global_load_dword v38, v[6:7], off offset:1024
	global_load_dword v39, v[6:7], off offset:2048
	global_load_dword v43, v[6:7], off offset:3072
	global_load_dword v44, v[10:11], off offset:1024
	global_load_dword v45, v[10:11], off offset:2048
	global_load_dword v46, v[10:11], off offset:3072
	global_load_dword v47, v[8:9], off offset:1024
	global_load_dword v48, v[8:9], off offset:2048
	v_add_co_u32_e32 v14, vcc, s0, v4
	s_mov_b32 s0, 0x18206000
	s_nop 0
	v_addc_co_u32_e32 v15, vcc, 0, v5, vcc
	v_add_co_u32_e32 v6, vcc, s0, v4
	s_mov_b32 s0, 0x18207000
	s_nop 0
	v_addc_co_u32_e32 v7, vcc, 0, v5, vcc
	v_add_co_u32_e32 v10, vcc, s0, v4
	s_mov_b32 s0, 0x18208000
	s_nop 0
	v_addc_co_u32_e32 v11, vcc, 0, v5, vcc
	global_load_dword v49, v[12:13], off offset:2048
	global_load_dword v50, v[12:13], off offset:3072
	global_load_dword v51, v[14:15], off offset:-4096
	global_load_dword v52, v[14:15], off
	global_load_dword v53, v[14:15], off offset:1024
	global_load_dword v54, v[14:15], off offset:2048
	global_load_dword v55, v[14:15], off offset:3072
	global_load_dword v56, v[10:11], off offset:-4096
	v_add_co_u32_e32 v12, vcc, s0, v4
	s_mov_b32 s0, 0x18209000
	s_nop 0
	v_addc_co_u32_e32 v13, vcc, 0, v5, vcc
	v_add_co_u32_e32 v14, vcc, s0, v4
	s_mov_b32 s0, 0x1820a000
	s_nop 0
	v_addc_co_u32_e32 v15, vcc, 0, v5, vcc
	global_load_dword v57, v[10:11], off
	global_load_dword v58, v[10:11], off offset:1024
	global_load_dword v59, v[10:11], off offset:2048
	global_load_dword v60, v[10:11], off offset:3072
	global_load_dword v61, v[14:15], off offset:-4096
	global_load_dword v62, v[14:15], off
	global_load_dword v63, v[14:15], off offset:1024
	global_load_dword v64, v[14:15], off offset:2048
	v_add_co_u32_e32 v10, vcc, s0, v4
	s_mov_b32 s0, 0x1820b000
	s_nop 0
	v_addc_co_u32_e32 v11, vcc, 0, v5, vcc
	v_add_co_u32_e32 v16, vcc, s0, v4
	s_mov_b32 s0, 0x1820c000
	s_nop 0
	v_addc_co_u32_e32 v17, vcc, 0, v5, vcc
	global_load_dword v65, v[8:9], off offset:3072
	global_load_dword v66, v[6:7], off offset:1024
	global_load_dword v67, v[6:7], off offset:2048
	global_load_dword v68, v[6:7], off offset:3072
	global_load_dword v69, v[12:13], off offset:1024
	global_load_dword v70, v[12:13], off offset:2048
	global_load_dword v71, v[12:13], off offset:3072
	global_load_dword v72, v[10:11], off offset:1024
	v_add_co_u32_e32 v6, vcc, s0, v4
	s_mov_b32 s0, 0x1820d000
	s_nop 0
	v_addc_co_u32_e32 v7, vcc, 0, v5, vcc
	v_add_co_u32_e32 v20, vcc, s0, v4
	s_mov_b32 s0, 0x1820e000
	s_nop 0
	v_addc_co_u32_e32 v21, vcc, 0, v5, vcc
	v_add_co_u32_e32 v8, vcc, s0, v4
	s_mov_b32 s0, 0x1820f000
	s_nop 0
	v_addc_co_u32_e32 v9, vcc, 0, v5, vcc
	v_add_co_u32_e32 v4, vcc, s0, v4
	s_mov_b32 s0, 0xbfb8aa3b
	global_load_dword v73, v[14:15], off offset:3072
	global_load_dword v74, v[16:17], off offset:-4096
	global_load_dword v42, v[16:17], off
	global_load_dword v41, v[16:17], off offset:1024
	global_load_dword v40, v[16:17], off offset:2048
	global_load_dword v36, v[16:17], off offset:3072
	global_load_dword v34, v[20:21], off offset:-4096
	global_load_dword v25, v[20:21], off
	global_load_dword v75, v[10:11], off offset:2048
	global_load_dword v76, v[10:11], off offset:3072
	global_load_dword v37, v[6:7], off offset:1024
	global_load_dword v33, v[6:7], off offset:2048
	global_load_dword v31, v[6:7], off offset:3072
	global_load_dword v19, v[8:9], off offset:1024
	global_load_dword v16, v[8:9], off offset:2048
	global_load_dword v14, v[8:9], off offset:3072
	v_addc_co_u32_e32 v5, vcc, 0, v5, vcc
	global_load_dword v30, v[20:21], off offset:1024
	global_load_dword v28, v[20:21], off offset:2048
	global_load_dword v26, v[20:21], off offset:3072
	global_load_dword v24, v[4:5], off offset:-4096
	global_load_dword v15, v[4:5], off
	global_load_dword v13, v[4:5], off offset:1024
	global_load_dword v10, v[4:5], off offset:2048
	global_load_dword v9, v[4:5], off offset:3072
	s_ashr_i32 s5, s4, 31
	s_waitcnt vmcnt(62)
; __device__ __forceinline__ void phase_shift_cum(const Args& A, int gtid, int NGT, int gw, int lane) {
;     ...
;         float loc = 0.f;
; #pragma unroll
;         for (int i = 0; i < 64; ++i) { const float z = zv[i] + bf; loc += fminf(z, 0.f) - 0.6931471805599453f * __builtin_amdgcn_logf(1.0f + __builtin_amdgcn_exp2f(-1.4426950408889634f * fabsf(z))); zv[i] = loc; }
	v_add_f32_e32 v0, v3, v0
	v_mul_f32_e64 v6, |v0|, s0
	v_exp_f32_e32 v6, v6
	v_min_f32_e32 v0, 0, v0
	s_waitcnt vmcnt(60)
	v_add_f32_e32 v17, v3, v23
	s_waitcnt vmcnt(55)
	v_add_f32_e32 v5, v3, v38
	v_add_f32_e32 v4, 1.0, v6
	v_mul_f32_e64 v6, |v5|, s0
	v_log_f32_e32 v4, v4
	v_exp_f32_e32 v6, v6
	s_waitcnt vmcnt(53)
	v_add_f32_e32 v8, v3, v43
	v_mul_f32_e64 v11, |v8|, s0
	v_fmac_f32_e32 v0, 0xbf317218, v4
	v_min_f32_e32 v4, 0, v5
	v_add_f32_e32 v5, 1.0, v6
	v_add_f32_e32 v6, v3, v39
	v_mul_f32_e64 v7, |v6|, s0
	v_log_f32_e32 v5, v5
	v_exp_f32_e32 v7, v7
	v_exp_f32_e32 v11, v11
	s_waitcnt vmcnt(52)
	v_add_f32_e32 v21, v3, v44
	v_fmac_f32_e32 v4, 0xbf317218, v5
	v_add_f32_e32 v5, 1.0, v7
	v_log_f32_e32 v7, v5
	v_add_f32_e32 v5, 1.0, v11
	v_log_f32_e32 v11, v5
	v_min_f32_e32 v5, 0, v6
	v_fmac_f32_e32 v5, 0xbf317218, v7
	v_min_f32_e32 v6, 0, v8
	v_add_f32_e32 v7, v3, v18
	v_fmac_f32_e32 v6, 0xbf317218, v11
	v_mul_f32_e64 v8, |v7|, s0
	v_add_f32_e32 v11, v3, v22
	v_exp_f32_e32 v8, v8
	v_mul_f32_e64 v12, |v11|, s0
	v_exp_f32_e32 v12, v12
	v_mul_f32_e64 v18, |v17|, s0
	v_add_f32_e32 v8, 1.0, v8
	v_log_f32_e32 v8, v8
	v_add_f32_e32 v12, 1.0, v12
	v_exp_f32_e32 v18, v18
	v_log_f32_e32 v12, v12
	v_min_f32_e32 v7, 0, v7
	v_fmac_f32_e32 v7, 0xbf317218, v8
	v_min_f32_e32 v8, 0, v11
	v_add_f32_e32 v11, 1.0, v18
	v_add_f32_e32 v18, v3, v27
	v_fmac_f32_e32 v8, 0xbf317218, v12
	v_log_f32_e32 v12, v11
	v_mul_f32_e64 v11, |v18|, s0
	v_exp_f32_e32 v20, v11
	v_min_f32_e32 v11, 0, v17
	v_fmac_f32_e32 v11, 0xbf317218, v12
	v_min_f32_e32 v12, 0, v18
	v_add_f32_e32 v18, v3, v29
	v_add_f32_e32 v17, 1.0, v20
	v_mul_f32_e64 v20, |v18|, s0
	v_log_f32_e32 v17, v17
	v_exp_f32_e32 v20, v20
	v_mul_f32_e64 v22, |v21|, s0
	v_exp_f32_e32 v22, v22
	v_fmac_f32_e32 v12, 0xbf317218, v17
	v_add_f32_e32 v17, 1.0, v20
	v_log_f32_e32 v20, v17
	v_add_f32_e32 v17, 1.0, v22
	v_log_f32_e32 v22, v17
	v_min_f32_e32 v17, 0, v18
	v_fmac_f32_e32 v17, 0xbf317218, v20
	v_min_f32_e32 v18, 0, v21
	s_waitcnt vmcnt(51)
	v_add_f32_e32 v20, v3, v45
	v_fmac_f32_e32 v18, 0xbf317218, v22
	v_mul_f32_e64 v21, |v20|, s0
	s_waitcnt vmcnt(50)
	v_add_f32_e32 v22, v3, v46
	v_exp_f32_e32 v21, v21
	v_mul_f32_e64 v23, |v22|, s0
	v_exp_f32_e32 v23, v23
	v_add_f32_e32 v27, v3, v32
	v_add_f32_e32 v21, 1.0, v21
	v_mul_f32_e64 v29, |v27|, s0
	v_log_f32_e32 v21, v21
	v_add_f32_e32 v23, 1.0, v23
	v_exp_f32_e32 v29, v29
	v_log_f32_e32 v23, v23
	v_min_f32_e32 v20, 0, v20
	v_fmac_f32_e32 v20, 0xbf317218, v21
	v_min_f32_e32 v21, 0, v22
	v_add_f32_e32 v22, 1.0, v29
	v_add_f32_e32 v29, v3, v35
	v_fmac_f32_e32 v21, 0xbf317218, v23
	v_log_f32_e32 v23, v22
	v_mul_f32_e64 v22, |v29|, s0
	v_exp_f32_e32 v32, v22
	v_min_f32_e32 v22, 0, v27
	v_fmac_f32_e32 v22, 0xbf317218, v23
	v_min_f32_e32 v23, 0, v29
	s_waitcnt vmcnt(47)
	v_add_f32_e32 v29, v3, v49
	v_add_f32_e32 v27, 1.0, v32
	v_mul_f32_e64 v32, |v29|, s0
	s_waitcnt vmcnt(46)
	v_add_f32_e32 v35, v3, v50
	v_log_f32_e32 v27, v27
	v_exp_f32_e32 v32, v32
	v_mul_f32_e64 v38, |v35|, s0
	v_exp_f32_e32 v38, v38
	v_fmac_f32_e32 v23, 0xbf317218, v27
	v_add_f32_e32 v27, 1.0, v32
	v_log_f32_e32 v32, v27
	v_add_f32_e32 v27, 1.0, v38
	v_log_f32_e32 v38, v27
	v_min_f32_e32 v27, 0, v29
	v_fmac_f32_e32 v27, 0xbf317218, v32
	v_min_f32_e32 v29, 0, v35
	s_waitcnt vmcnt(45)
	v_add_f32_e32 v32, v3, v51
	v_fmac_f32_e32 v29, 0xbf317218, v38
	v_mul_f32_e64 v35, |v32|, s0
	v_add_f32_e32 v38, v3, v47
	v_exp_f32_e32 v35, v35
	v_mul_f32_e64 v39, |v38|, s0
	v_exp_f32_e32 v39, v39
	v_add_f32_e32 v43, v3, v48
	v_add_f32_e32 v35, 1.0, v35
	v_mul_f32_e64 v44, |v43|, s0
	v_log_f32_e32 v35, v35
	v_add_f32_e32 v39, 1.0, v39
	v_exp_f32_e32 v44, v44
	v_log_f32_e32 v39, v39
	v_min_f32_e32 v32, 0, v32
	v_fmac_f32_e32 v32, 0xbf317218, v35
	v_min_f32_e32 v35, 0, v38
	v_add_f32_e32 v38, 1.0, v44
	s_waitcnt vmcnt(31)
	v_add_f32_e32 v44, v3, v65
	v_fmac_f32_e32 v35, 0xbf317218, v39
	v_log_f32_e32 v39, v38
	v_mul_f32_e64 v38, |v44|, s0
	v_exp_f32_e32 v45, v38
	v_min_f32_e32 v38, 0, v43
	v_fmac_f32_e32 v38, 0xbf317218, v39
	v_min_f32_e32 v39, 0, v44
	v_add_f32_e32 v44, v3, v52
	v_add_f32_e32 v43, 1.0, v45
	v_mul_f32_e64 v45, |v44|, s0
	v_add_f32_e32 v46, v3, v53
	v_log_f32_e32 v43, v43
	v_exp_f32_e32 v45, v45
	v_mul_f32_e64 v47, |v46|, s0
	v_exp_f32_e32 v47, v47
	v_fmac_f32_e32 v39, 0xbf317218, v43
	v_add_f32_e32 v43, 1.0, v45
	v_log_f32_e32 v45, v43
	v_add_f32_e32 v43, 1.0, v47
	v_log_f32_e32 v47, v43
	v_min_f32_e32 v43, 0, v44
	v_fmac_f32_e32 v43, 0xbf317218, v45
	v_min_f32_e32 v44, 0, v46
	v_add_f32_e32 v45, v3, v54
	v_fmac_f32_e32 v44, 0xbf317218, v47
	v_mul_f32_e64 v46, |v45|, s0
	v_add_f32_e32 v47, v3, v55
	v_exp_f32_e32 v46, v46
	v_mul_f32_e64 v48, |v47|, s0
	v_exp_f32_e32 v48, v48
	v_add_f32_e32 v49, v3, v56
	v_add_f32_e32 v46, 1.0, v46
	v_log_f32_e32 v46, v46
	v_add_f32_e32 v48, 1.0, v48
	v_log_f32_e32 v48, v48
	v_mul_f32_e64 v50, |v49|, s0
	v_exp_f32_e32 v50, v50
	v_min_f32_e32 v45, 0, v45
	v_fmac_f32_e32 v45, 0xbf317218, v46
	v_min_f32_e32 v46, 0, v47
	v_fmac_f32_e32 v46, 0xbf317218, v48
	s_waitcnt vmcnt(30)
	v_add_f32_e32 v48, v3, v66
	v_add_f32_e32 v47, 1.0, v50
	v_mul_f32_e64 v50, |v48|, s0
	v_log_f32_e32 v47, v47
	v_exp_f32_e32 v50, v50
	v_min_f32_e32 v49, 0, v49
	s_waitcnt vmcnt(28)
; __device__ __forceinline__ void phase_shift_cum(const Args& A, int gtid, int NGT, int gw, int lane) {
;     ...
;         for (int i = 0; i < 64; ++i) { const float z = zv[i] + bf; loc += fminf(z, 0.f) - 0.6931471805599453f * __builtin_amdgcn_logf(1.0f + __builtin_amdgcn_exp2f(-1.4426950408889634f * fabsf(z))); zv[i] = loc; }
	v_add_f32_e32 v52, v3, v68
	v_fmac_f32_e32 v49, 0xbf317218, v47
	v_min_f32_e32 v47, 0, v48
	v_add_f32_e32 v48, 1.0, v50
	v_add_f32_e32 v50, v3, v67
	v_mul_f32_e64 v51, |v50|, s0
	v_log_f32_e32 v48, v48
	v_exp_f32_e32 v51, v51
	v_mul_f32_e64 v53, |v52|, s0
	v_exp_f32_e32 v53, v53
	v_fmac_f32_e32 v47, 0xbf317218, v48
	v_add_f32_e32 v48, 1.0, v51
	v_log_f32_e32 v48, v48
	v_add_f32_e32 v51, 1.0, v53
	v_log_f32_e32 v51, v51
	v_min_f32_e32 v50, 0, v50
	v_fmac_f32_e32 v50, 0xbf317218, v48
	v_min_f32_e32 v48, 0, v52
	v_fmac_f32_e32 v48, 0xbf317218, v51
	v_add_f32_e32 v51, v3, v57
	v_mul_f32_e64 v52, |v51|, s0
	v_add_f32_e32 v53, v3, v58
	v_exp_f32_e32 v52, v52
	v_mul_f32_e64 v54, |v53|, s0
	v_exp_f32_e32 v54, v54
	v_add_f32_e32 v55, v3, v59
	v_add_f32_e32 v52, 1.0, v52
	v_log_f32_e32 v52, v52
	v_add_f32_e32 v54, 1.0, v54
	v_log_f32_e32 v54, v54
	v_mul_f32_e64 v56, |v55|, s0
	v_exp_f32_e32 v56, v56
	v_min_f32_e32 v51, 0, v51
	v_fmac_f32_e32 v51, 0xbf317218, v52
	v_min_f32_e32 v52, 0, v53
	v_fmac_f32_e32 v52, 0xbf317218, v54
	v_add_f32_e32 v54, v3, v60
	v_add_f32_e32 v53, 1.0, v56
	v_mul_f32_e64 v56, |v54|, s0
	v_log_f32_e32 v53, v53
	v_exp_f32_e32 v56, v56
	v_min_f32_e32 v55, 0, v55
	s_waitcnt vmcnt(27)
	v_add_f32_e32 v58, v3, v69
	v_fmac_f32_e32 v55, 0xbf317218, v53
	v_min_f32_e32 v53, 0, v54
	v_add_f32_e32 v54, 1.0, v56
	v_add_f32_e32 v56, v3, v61
	v_mul_f32_e64 v57, |v56|, s0
	v_log_f32_e32 v54, v54
	v_exp_f32_e32 v57, v57
	v_mul_f32_e64 v59, |v58|, s0
	v_exp_f32_e32 v59, v59
	v_fmac_f32_e32 v53, 0xbf317218, v54
	v_add_f32_e32 v54, 1.0, v57
	v_log_f32_e32 v54, v54
	v_add_f32_e32 v57, 1.0, v59
	v_log_f32_e32 v57, v57
	v_min_f32_e32 v56, 0, v56
	v_fmac_f32_e32 v56, 0xbf317218, v54
	v_min_f32_e32 v54, 0, v58
	v_fmac_f32_e32 v54, 0xbf317218, v57
	s_waitcnt vmcnt(26)
	v_add_f32_e32 v57, v3, v70
	v_mul_f32_e64 v58, |v57|, s0
	s_waitcnt vmcnt(25)
	v_add_f32_e32 v59, v3, v71
	v_exp_f32_e32 v58, v58
	v_mul_f32_e64 v60, |v59|, s0
	v_exp_f32_e32 v60, v60
	v_add_f32_e32 v61, v3, v62
	v_add_f32_e32 v58, 1.0, v58
	v_log_f32_e32 v58, v58
	v_add_f32_e32 v60, 1.0, v60
	v_log_f32_e32 v60, v60
	v_mul_f32_e64 v62, |v61|, s0
	v_exp_f32_e32 v62, v62
	v_min_f32_e32 v57, 0, v57
	v_fmac_f32_e32 v57, 0xbf317218, v58
	v_min_f32_e32 v58, 0, v59
	v_fmac_f32_e32 v58, 0xbf317218, v60
	v_add_f32_e32 v60, v3, v63
	v_add_f32_e32 v59, 1.0, v62
	v_mul_f32_e64 v62, |v60|, s0
	v_log_f32_e32 v59, v59
	v_exp_f32_e32 v62, v62
	v_min_f32_e32 v61, 0, v61
	s_waitcnt vmcnt(15)
	v_add_f32_e32 v67, v3, v75
	v_fmac_f32_e32 v61, 0xbf317218, v59
	v_min_f32_e32 v59, 0, v60
	v_add_f32_e32 v60, 1.0, v62
	v_add_f32_e32 v62, v3, v64
	v_mul_f32_e64 v63, |v62|, s0
	v_add_f32_e32 v64, v3, v73
	v_log_f32_e32 v60, v60
	v_exp_f32_e32 v63, v63
	v_mul_f32_e64 v65, |v64|, s0
	v_exp_f32_e32 v65, v65
	v_fmac_f32_e32 v59, 0xbf317218, v60
	v_add_f32_e32 v60, 1.0, v63
	v_log_f32_e32 v60, v60
	v_add_f32_e32 v63, 1.0, v65
	v_log_f32_e32 v63, v63
	v_min_f32_e32 v62, 0, v62
	v_fmac_f32_e32 v62, 0xbf317218, v60
	v_min_f32_e32 v60, 0, v64
	v_fmac_f32_e32 v60, 0xbf317218, v63
	v_add_f32_e32 v63, v3, v74
	v_mul_f32_e64 v64, |v63|, s0
	v_add_f32_e32 v65, v3, v72
	v_exp_f32_e32 v64, v64
	v_mul_f32_e64 v66, |v65|, s0
	v_exp_f32_e32 v66, v66
	v_mul_f32_e64 v68, |v67|, s0
	v_add_f32_e32 v64, 1.0, v64
	v_log_f32_e32 v64, v64
	v_add_f32_e32 v66, 1.0, v66
	v_log_f32_e32 v66, v66
	v_exp_f32_e32 v68, v68
	v_min_f32_e32 v63, 0, v63
	v_fmac_f32_e32 v63, 0xbf317218, v64
	v_min_f32_e32 v64, 0, v65
	v_fmac_f32_e32 v64, 0xbf317218, v66
	s_waitcnt vmcnt(14)
	v_add_f32_e32 v66, v3, v76
	v_add_f32_e32 v65, 1.0, v68
	v_mul_f32_e64 v68, |v66|, s0
	v_log_f32_e32 v65, v65
	v_exp_f32_e32 v68, v68
	v_min_f32_e32 v67, 0, v67
	v_add_f32_e32 v42, v3, v42
	v_fmac_f32_e32 v67, 0xbf317218, v65
	v_min_f32_e32 v65, 0, v66
	v_add_f32_e32 v66, 1.0, v68
	v_mul_f32_e64 v68, |v42|, s0
	v_log_f32_e32 v66, v66
	v_exp_f32_e32 v68, v68
	v_add_f32_e32 v41, v3, v41
	v_mul_f32_e64 v69, |v41|, s0
	v_exp_f32_e32 v69, v69
	v_fmac_f32_e32 v65, 0xbf317218, v66
	v_add_f32_e32 v66, 1.0, v68
	v_log_f32_e32 v66, v66
	v_add_f32_e32 v68, 1.0, v69
	v_min_f32_e32 v69, 0, v42
	v_add_f32_e32 v40, v3, v40
	v_add_f32_e32 v36, v3, v36
	v_fmac_f32_e32 v69, 0xbf317218, v66
	v_min_f32_e32 v66, 0, v41
	v_mul_f32_e64 v41, |v40|, s0
	v_mul_f32_e64 v42, |v36|, s0
	v_log_f32_e32 v68, v68
	v_exp_f32_e32 v41, v41
	v_exp_f32_e32 v42, v42
	v_add_f32_e32 v34, v3, v34
	v_fmac_f32_e32 v66, 0xbf317218, v68
	v_min_f32_e32 v68, 0, v40
	v_add_f32_e32 v40, 1.0, v41
	v_add_f32_e32 v41, 1.0, v42
	v_mul_f32_e64 v42, |v34|, s0
	v_exp_f32_e32 v42, v42
	v_min_f32_e32 v70, 0, v36
	v_log_f32_e32 v40, v40
	s_waitcnt vmcnt(13)
	v_add_f32_e32 v37, v3, v37
	v_add_f32_e32 v36, 1.0, v42
	v_log_f32_e32 v36, v36
	v_min_f32_e32 v71, 0, v34
	s_waitcnt vmcnt(12)
	v_add_f32_e32 v33, v3, v33
	s_waitcnt vmcnt(11)
	v_add_f32_e32 v31, v3, v31
	v_add_f32_e32 v25, v3, v25
	s_waitcnt vmcnt(7)
	v_add_f32_e32 v30, v3, v30
	v_fmac_f32_e32 v68, 0xbf317218, v40
	v_mul_f32_e64 v40, |v37|, s0
	v_fmac_f32_e32 v71, 0xbf317218, v36
	v_min_f32_e32 v72, 0, v37
	v_mul_f32_e64 v36, |v33|, s0
	v_mul_f32_e64 v37, |v31|, s0
	v_min_f32_e32 v73, 0, v33
	v_min_f32_e32 v74, 0, v31
	v_mul_f32_e64 v31, |v25|, s0
	v_mul_f32_e64 v33, |v30|, s0
	v_exp_f32_e32 v31, v31
	v_exp_f32_e32 v33, v33
	s_waitcnt vmcnt(6)
	v_add_f32_e32 v28, v3, v28
	s_waitcnt vmcnt(5)
	v_add_f32_e32 v26, v3, v26
	s_waitcnt vmcnt(4)
; __device__ __forceinline__ void phase_shift_cum(const Args& A, int gtid, int NGT, int gw, int lane) {
;     ...
;         for (int i = 0; i < 64; ++i) { const float z = zv[i] + bf; loc += fminf(z, 0.f) - 0.6931471805599453f * __builtin_amdgcn_logf(1.0f + __builtin_amdgcn_exp2f(-1.4426950408889634f * fabsf(z))); zv[i] = loc; }
;         float incl = loc;
; #pragma unroll
;         for (int o = 1; o < 64; o <<= 1) { const float n = __shfl_up(incl, o); if (lane >= o) incl += n; }
	v_add_f32_e32 v24, v3, v24
	v_add_f32_e32 v19, v3, v19
	v_add_f32_e32 v16, v3, v16
	v_add_f32_e32 v14, v3, v14
	v_min_f32_e32 v75, 0, v25
	v_add_f32_e32 v25, 1.0, v31
	v_add_f32_e32 v31, 1.0, v33
	v_mul_f32_e64 v33, |v28|, s0
	v_min_f32_e32 v76, 0, v30
	v_mul_f32_e64 v30, |v26|, s0
	v_min_f32_e32 v77, 0, v28
	v_min_f32_e32 v78, 0, v26
	v_mul_f32_e64 v26, |v24|, s0
	v_mul_f32_e64 v28, |v19|, s0
	v_min_f32_e32 v79, 0, v24
	v_min_f32_e32 v80, 0, v19
	v_mul_f32_e64 v19, |v16|, s0
	v_mul_f32_e64 v24, |v14|, s0
	v_exp_f32_e32 v19, v19
	v_exp_f32_e32 v24, v24
	s_waitcnt vmcnt(3)
	v_add_f32_e32 v15, v3, v15
	v_min_f32_e32 v81, 0, v16
	v_add_f32_e32 v16, 1.0, v19
	v_add_f32_e32 v19, 1.0, v24
	v_mul_f32_e64 v24, |v15|, s0
	v_log_f32_e32 v16, v16
	v_exp_f32_e32 v24, v24
	s_waitcnt vmcnt(2)
	v_add_f32_e32 v13, v3, v13
	s_waitcnt vmcnt(1)
	v_add_f32_e32 v10, v3, v10
	s_waitcnt vmcnt(0)
	v_add_f32_e32 v3, v3, v9
	v_mul_f32_e64 v9, |v3|, s0
	v_fmac_f32_e32 v81, 0xbf317218, v16
	v_min_f32_e32 v82, 0, v14
	v_add_f32_e32 v14, 1.0, v24
	v_mul_f32_e64 v16, |v13|, s0
	v_exp_f32_e32 v9, v9
	v_log_f32_e32 v14, v14
	v_exp_f32_e32 v16, v16
	v_min_f32_e32 v83, 0, v15
	v_add_f32_e32 v9, 1.0, v9
	v_fmac_f32_e32 v83, 0xbf317218, v14
	v_min_f32_e32 v84, 0, v13
	v_add_f32_e32 v13, 1.0, v16
	v_mul_f32_e64 v14, |v10|, s0
	v_log_f32_e32 v9, v9
	v_log_f32_e32 v13, v13
	v_exp_f32_e32 v14, v14
	v_min_f32_e32 v3, 0, v3
	v_fmac_f32_e32 v3, 0xbf317218, v9
	v_mbcnt_lo_u32_b32 v9, -1, 0
	v_fmac_f32_e32 v84, 0xbf317218, v13
	v_add_f32_e32 v13, 1.0, v14
	v_mbcnt_hi_u32_b32 v86, -1, v9
	v_add_f32_e32 v14, 0, v0
	v_and_b32_e32 v87, 64, v86
	v_add_u32_e32 v9, -1, v86
	v_add_f32_e32 v15, v14, v4
	v_log_f32_e32 v25, v25
	v_exp_f32_e32 v33, v33
	v_cmp_lt_i32_e32 vcc, v9, v87
	v_add_f32_e32 v4, v15, v5
	v_add_f32_e32 v5, v4, v6
	v_cndmask_b32_e32 v9, v9, v86, vcc
	v_lshlrev_b32_e32 v88, 2, v9
	v_add_u32_e32 v9, -2, v86
	v_add_f32_e32 v6, v5, v7
	v_cmp_lt_i32_e32 vcc, v9, v87
	v_add_f32_e32 v7, v6, v8
	v_fmac_f32_e32 v75, 0xbf317218, v25
	v_add_f32_e32 v25, 1.0, v33
	v_cndmask_b32_e32 v9, v9, v86, vcc
	v_add_f32_e32 v8, v7, v11
	v_log_f32_e32 v25, v25
	v_exp_f32_e32 v30, v30
	v_log_f32_e32 v13, v13
	v_lshlrev_b32_e32 v89, 2, v9
	v_add_f32_e32 v9, v8, v12
	v_min_f32_e32 v85, 0, v10
	v_add_f32_e32 v10, v9, v17
	v_add_f32_e32 v11, v10, v18
	v_add_f32_e32 v12, v11, v20
	v_fmac_f32_e32 v77, 0xbf317218, v25
	v_add_f32_e32 v25, 1.0, v30
	v_log_f32_e32 v19, v19
	v_fmac_f32_e32 v85, 0xbf317218, v13
	v_add_f32_e32 v13, v12, v21
	v_log_f32_e32 v25, v25
	v_exp_f32_e32 v26, v26
	v_add_f32_e32 v16, v13, v22
	v_exp_f32_e32 v28, v28
	v_add_f32_e32 v17, v16, v23
	v_add_f32_e32 v18, v17, v27
	v_fmac_f32_e32 v82, 0xbf317218, v19
	v_add_f32_e32 v19, v18, v29
	v_exp_f32_e32 v40, v40
	v_fmac_f32_e32 v78, 0xbf317218, v25
	v_add_f32_e32 v25, 1.0, v26
	v_add_f32_e32 v20, v19, v32
	v_log_f32_e32 v25, v25
	v_add_f32_e32 v26, 1.0, v28
	v_add_f32_e32 v21, v20, v35
	v_log_f32_e32 v26, v26
	v_add_f32_e32 v22, v21, v38
	v_add_f32_e32 v23, v22, v39
	v_add_f32_e32 v34, 1.0, v40
	v_add_f32_e32 v24, v23, v43
	v_log_f32_e32 v34, v34
	v_exp_f32_e32 v36, v36
	v_fmac_f32_e32 v79, 0xbf317218, v25
	v_add_f32_e32 v25, v24, v44
	v_fmac_f32_e32 v80, 0xbf317218, v26
	v_add_f32_e32 v26, v25, v45
	v_exp_f32_e32 v37, v37
	v_log_f32_e32 v31, v31
	v_add_f32_e32 v27, v26, v46
	v_add_f32_e32 v28, v27, v49
	v_fmac_f32_e32 v72, 0xbf317218, v34
	v_add_f32_e32 v34, 1.0, v36
	v_add_f32_e32 v29, v28, v47
	v_log_f32_e32 v34, v34
	v_add_f32_e32 v30, v29, v50
	v_add_f32_e32 v36, 1.0, v37
	v_fmac_f32_e32 v76, 0xbf317218, v31
	v_add_f32_e32 v31, v30, v48
	v_log_f32_e32 v36, v36
	v_add_f32_e32 v32, v31, v51
	v_add_f32_e32 v33, v32, v52
	v_fmac_f32_e32 v73, 0xbf317218, v34
	v_add_f32_e32 v34, v33, v55
	v_add_f32_e32 v35, v34, v53
	v_fmac_f32_e32 v74, 0xbf317218, v36
	v_add_f32_e32 v36, v35, v56
	v_log_f32_e32 v41, v41
	v_add_f32_e32 v37, v36, v54
	v_add_f32_e32 v38, v37, v57
	v_add_f32_e32 v39, v38, v58
	v_add_f32_e32 v40, v39, v61
	v_fmac_f32_e32 v70, 0xbf317218, v41
	v_add_f32_e32 v41, v40, v59
	v_add_f32_e32 v42, v41, v62
	v_add_f32_e32 v43, v42, v60
	v_add_f32_e32 v44, v43, v63
	v_add_f32_e32 v45, v44, v64
	v_add_f32_e32 v46, v45, v67
	v_add_f32_e32 v47, v46, v65
	v_add_f32_e32 v48, v47, v69
	v_add_f32_e32 v49, v48, v66
	v_add_f32_e32 v50, v49, v68
	v_add_f32_e32 v51, v50, v70
	v_add_f32_e32 v52, v51, v71
	v_add_f32_e32 v53, v52, v72
	v_add_f32_e32 v54, v53, v73
	v_add_f32_e32 v55, v54, v74
	v_add_f32_e32 v56, v55, v75
	v_add_f32_e32 v57, v56, v76
	v_add_f32_e32 v58, v57, v77
	v_add_f32_e32 v59, v58, v78
	v_add_f32_e32 v60, v59, v79
	v_add_f32_e32 v61, v60, v80
	v_add_f32_e32 v62, v61, v81
	v_add_f32_e32 v63, v62, v82
	v_add_f32_e32 v64, v63, v83
	v_add_f32_e32 v65, v64, v84
	v_add_f32_e32 v66, v65, v85
	v_add_f32_e32 v67, v66, v3
	ds_bpermute_b32 v0, v88, v67
	v_add_u32_e32 v90, -4, v86
	v_cmp_lt_i32_e32 vcc, v90, v87
	v_add_u32_e32 v68, -8, v86
	v_add_u32_e32 v70, -16, v86
	v_cndmask_b32_e32 v3, v90, v86, vcc
	s_waitcnt lgkmcnt(0)
; __device__ __forceinline__ void phase_shift_cum(const Args& A, int gtid, int NGT, int gw, int lane) {
;     ...
;         for (int o = 1; o < 64; o <<= 1) { const float n = __shfl_up(incl, o); if (lane >= o) incl += n; }
;         const float off = incl - loc; float* dst = CUM + (size_t)gw * T + lane * 64;
; #pragma unroll
;         for (int i = 0; i < 64; i += 4) *(f32x4*)(dst + i) = (f32x4){zv[i] + off, zv[i + 1] + off, zv[i + 2] + off, zv[i + 3] + off};
	v_add_f32_e32 v0, v67, v0
	v_cmp_eq_u32_e32 vcc, 0, v2
	v_lshlrev_b32_e32 v3, 2, v3
	s_lshl_b64 s[0:1], s[4:5], 14
	v_cndmask_b32_e32 v0, v0, v67, vcc
	ds_bpermute_b32 v69, v89, v0
	v_cmp_lt_i32_e32 vcc, v68, v87
	s_add_u32 s0, s34, s0
	s_addc_u32 s1, s35, s1
	v_cndmask_b32_e32 v68, v68, v86, vcc
	s_waitcnt lgkmcnt(0)
	v_add_f32_e32 v69, v0, v69
	v_cmp_gt_u32_e32 vcc, 2, v2
	v_lshlrev_b32_e32 v68, 2, v68
	s_nop 0
	v_cndmask_b32_e32 v0, v69, v0, vcc
	ds_bpermute_b32 v3, v3, v0
	v_cmp_lt_i32_e32 vcc, v70, v87
	s_waitcnt lgkmcnt(0)
	v_add_f32_e32 v3, v0, v3
	v_cndmask_b32_e32 v69, v70, v86, vcc
	v_cmp_gt_u32_e32 vcc, 4, v2
	v_subrev_u32_e32 v70, 32, v86
	v_lshlrev_b32_e32 v69, 2, v69
	v_cndmask_b32_e32 v0, v3, v0, vcc
	ds_bpermute_b32 v3, v68, v0
	v_cmp_lt_i32_e32 vcc, v70, v87
	s_waitcnt lgkmcnt(0)
	v_add_f32_e32 v3, v0, v3
	v_cndmask_b32_e32 v68, v70, v86, vcc
	v_cmp_gt_u32_e32 vcc, 8, v2
	v_lshlrev_b32_e32 v68, 2, v68
	s_nop 0
	v_cndmask_b32_e32 v3, v3, v0, vcc
	ds_bpermute_b32 v69, v69, v3
	v_cmp_gt_u32_e32 vcc, 16, v2
	v_lshlrev_b32_e32 v0, 8, v2
	s_waitcnt lgkmcnt(0)
	v_add_f32_e32 v69, v3, v69
	v_cndmask_b32_e32 v3, v69, v3, vcc
	ds_bpermute_b32 v72, v68, v3
	v_lshl_add_u64 v[68:69], s[0:1], 0, v[0:1]
	v_cmp_gt_u32_e32 vcc, 32, v2
	s_mov_b64 s[0:1], 0x28800000
	v_lshl_add_u64 v[70:71], v[68:69], 0, s[0:1]
	s_waitcnt lgkmcnt(0)
	v_add_f32_e32 v0, v3, v72
	v_cndmask_b32_e32 v0, v0, v3, vcc
	v_sub_f32_e32 v72, v0, v67
	s_mov_b32 s0, 0x28800000
	v_pk_add_f32 v[2:3], v[4:5], v[72:73] op_sel_hi:[1,0]
	v_add_co_u32_e32 v4, vcc, s0, v68
	v_pk_add_f32 v[0:1], v[14:15], v[72:73] op_sel_hi:[1,0]
	s_nop 0
	v_addc_co_u32_e32 v5, vcc, 0, v69, vcc
	global_store_dwordx4 v[4:5], v[0:3], off
	s_nop 1
	v_pk_add_f32 v[2:3], v[8:9], v[72:73] op_sel_hi:[1,0]
	v_pk_add_f32 v[0:1], v[6:7], v[72:73] op_sel_hi:[1,0]
	global_store_dwordx4 v[70:71], v[0:3], off offset:16
	s_nop 1
	v_pk_add_f32 v[2:3], v[12:13], v[72:73] op_sel_hi:[1,0]
	v_pk_add_f32 v[0:1], v[10:11], v[72:73] op_sel_hi:[1,0]
	global_store_dwordx4 v[70:71], v[0:3], off offset:32
	s_nop 1
	v_pk_add_f32 v[2:3], v[18:19], v[72:73] op_sel_hi:[1,0]
	v_pk_add_f32 v[0:1], v[16:17], v[72:73] op_sel_hi:[1,0]
	global_store_dwordx4 v[70:71], v[0:3], off offset:48
	s_nop 1
	v_pk_add_f32 v[2:3], v[22:23], v[72:73] op_sel_hi:[1,0]
	v_pk_add_f32 v[0:1], v[20:21], v[72:73] op_sel_hi:[1,0]
	global_store_dwordx4 v[70:71], v[0:3], off offset:64
	s_nop 1
	v_pk_add_f32 v[2:3], v[26:27], v[72:73] op_sel_hi:[1,0]
	v_pk_add_f32 v[0:1], v[24:25], v[72:73] op_sel_hi:[1,0]
	global_store_dwordx4 v[70:71], v[0:3], off offset:80
	s_nop 1
	v_pk_add_f32 v[2:3], v[30:31], v[72:73] op_sel_hi:[1,0]
	v_pk_add_f32 v[0:1], v[28:29], v[72:73] op_sel_hi:[1,0]
	global_store_dwordx4 v[70:71], v[0:3], off offset:96
	s_nop 1
	v_pk_add_f32 v[2:3], v[34:35], v[72:73] op_sel_hi:[1,0]
	v_pk_add_f32 v[0:1], v[32:33], v[72:73] op_sel_hi:[1,0]
	global_store_dwordx4 v[70:71], v[0:3], off offset:112
	s_nop 1
	v_pk_add_f32 v[2:3], v[38:39], v[72:73] op_sel_hi:[1,0]
	v_pk_add_f32 v[0:1], v[36:37], v[72:73] op_sel_hi:[1,0]
	global_store_dwordx4 v[70:71], v[0:3], off offset:128
	s_nop 1
	v_pk_add_f32 v[2:3], v[42:43], v[72:73] op_sel_hi:[1,0]
	v_pk_add_f32 v[0:1], v[40:41], v[72:73] op_sel_hi:[1,0]
	global_store_dwordx4 v[70:71], v[0:3], off offset:144
	s_nop 1
	v_pk_add_f32 v[2:3], v[46:47], v[72:73] op_sel_hi:[1,0]
	v_pk_add_f32 v[0:1], v[44:45], v[72:73] op_sel_hi:[1,0]
	global_store_dwordx4 v[70:71], v[0:3], off offset:160
	s_nop 1
	v_pk_add_f32 v[2:3], v[50:51], v[72:73] op_sel_hi:[1,0]
	v_pk_add_f32 v[0:1], v[48:49], v[72:73] op_sel_hi:[1,0]
	global_store_dwordx4 v[70:71], v[0:3], off offset:176
	s_nop 1
	v_pk_add_f32 v[2:3], v[54:55], v[72:73] op_sel_hi:[1,0]
	v_pk_add_f32 v[0:1], v[52:53], v[72:73] op_sel_hi:[1,0]
	global_store_dwordx4 v[70:71], v[0:3], off offset:192
	s_nop 1
	v_pk_add_f32 v[2:3], v[58:59], v[72:73] op_sel_hi:[1,0]
	v_pk_add_f32 v[0:1], v[56:57], v[72:73] op_sel_hi:[1,0]
	global_store_dwordx4 v[70:71], v[0:3], off offset:208
	s_nop 1
	v_pk_add_f32 v[2:3], v[62:63], v[72:73] op_sel_hi:[1,0]
	v_pk_add_f32 v[0:1], v[60:61], v[72:73] op_sel_hi:[1,0]
	global_store_dwordx4 v[70:71], v[0:3], off offset:224
	s_nop 1
	v_pk_add_f32 v[2:3], v[66:67], v[72:73] op_sel_hi:[1,0]
	v_pk_add_f32 v[0:1], v[64:65], v[72:73] op_sel_hi:[1,0]
	global_store_dwordx4 v[70:71], v[0:3], off offset:240

; __device__ __forceinline__ void phase_shift_cum(const Args& A, int gtid, int NGT, int gw, int lane) {
;     ...
;     const float* FL = (const float*)(ws + WS_FL); const float* b_f = A.in[14]; float* CUM = (float*)(ws + WS_CUM);
;     if (gw < BATCH * NH) {
;         const int b = gw / NH, h = gw % NH; const float bf = b_f[h];
;         const float* src = FL + ((size_t)b * T + lane * 64) * 256 + h; float zv[64];
; #pragma unroll
;         for (int i = 0; i < 64; ++i) zv[i] = src[(size_t)i * 256];
.LBB0_387:
	s_load_dword s0, s[62:63], 0xb8
	s_mov_b32 s1, s97
	s_waitcnt lgkmcnt(0)
	s_and_b32 s2, s0, 7
	s_cmp_lg_u32 s2, 0
	s_cbranch_scc1 .Lcm_vcu
	s_lshr_b32 s2, s0, 3
	s_and_b32 s3, s97, 7
	s_mul_i32 s2, s2, s3
	s_lshr_b32 s3, s97, 3
	s_add_i32 s1, s2, s3
.Lcm_vcu:
	s_lshr_b32 s0, s36, 6
	s_lshl_b32 s2, s1, 3
	s_add_i32 s2, s2, s0
	s_cmp_lt_i32 s2, 48
	s_cbranch_scc0 .Lcm_skip
	s_mov_b64 s[88:89], s[4:5]
	s_mov_b64 s[90:91], s[6:7]
	s_mov_b64 s[92:93], s[22:23]
	s_mov_b32 s0, s36
	s_waitcnt vmcnt(0)
	v_mbcnt_lo_u32_b32 v14, -1, 0
	v_mbcnt_hi_u32_b32 v14, -1, v14
	v_add_u32_e32 v14, s36, v14
	s_ashr_i32 s0, s0, 6
	s_lshl_b32 s1, s1, 3
	s_add_i32 s4, s1, s0
	s_cmp_lt_i32 s4, 48
	s_cbranch_scc0 .Lcm_done
	s_mul_hi_i32 s0, s4, 0x2aaaaaab
	s_lshr_b32 s1, s0, 31
	s_ashr_i32 s0, s0, 2
	s_add_i32 s0, s0, s1
	s_load_dwordx16 s[8:23], s[62:63], 0x40
	s_mul_i32 s1, s0, 24
	s_sub_i32 s6, s4, s1
	s_ashr_i32 s7, s6, 31
	s_lshl_b64 s[6:7], s[6:7], 2
	s_waitcnt lgkmcnt(0)
	s_add_u32 s8, s20, s6
	s_addc_u32 s9, s21, s7
	s_ashr_i32 s1, s0, 31
	s_lshl_b64 s[0:1], s[0:1], 22
	v_and_b32_e32 v2, 63, v14
	s_add_u32 s0, s34, s0
	v_mov_b32_e32 v1, 0
	s_addc_u32 s1, s35, s1
	v_lshlrev_b32_e32 v0, 16, v2
	v_lshl_add_u64 v[4:5], s[0:1], 0, v[0:1]
	global_load_dword v3, v1, s[8:9]
	v_lshl_add_u64 v[4:5], v[4:5], 0, s[6:7]
	s_mov_b64 s[0:1], 0x18200000
	v_lshl_add_u64 v[6:7], v[4:5], 0, s[0:1]
	s_mov_b32 s0, 0x18201000
	v_add_co_u32_e32 v8, vcc, s0, v4
	s_mov_b32 s0, 0x18202000
	s_nop 0
	v_addc_co_u32_e32 v9, vcc, 0, v5, vcc
	v_add_co_u32_e32 v10, vcc, s0, v4
	s_mov_b32 s0, 0x18203000
	s_nop 0
	v_addc_co_u32_e32 v11, vcc, 0, v5, vcc
	v_add_co_u32_e32 v12, vcc, s0, v4
	s_mov_b32 s0, 0x18204000
	s_nop 0
	v_addc_co_u32_e32 v13, vcc, 0, v5, vcc
	global_load_dword v0, v[8:9], off offset:-4096
	global_load_dword v18, v[8:9], off
	global_load_dword v22, v[8:9], off offset:1024
	global_load_dword v23, v[8:9], off offset:2048
	global_load_dword v27, v[8:9], off offset:3072
	global_load_dword v29, v[12:13], off offset:-4096
	global_load_dword v32, v[12:13], off
	global_load_dword v35, v[12:13], off offset:1024
	v_add_co_u32_e32 v8, vcc, s0, v4
	s_mov_b32 s0, 0x18205000
	s_nop 0
	v_addc_co_u32_e32 v9, vcc, 0, v5, vcc
	global_load_dword v38, v[6:7], off offset:1024
	global_load_dword v39, v[6:7], off offset:2048
	global_load_dword v43, v[6:7], off offset:3072
	global_load_dword v44, v[10:11], off offset:1024
	global_load_dword v45, v[10:11], off offset:2048
	global_load_dword v46, v[10:11], off offset:3072
	global_load_dword v47, v[8:9], off offset:1024
	global_load_dword v48, v[8:9], off offset:2048
	v_add_co_u32_e32 v14, vcc, s0, v4
	s_mov_b32 s0, 0x18206000
	s_nop 0
	v_addc_co_u32_e32 v15, vcc, 0, v5, vcc
	v_add_co_u32_e32 v6, vcc, s0, v4
	s_mov_b32 s0, 0x18207000
	s_nop 0
	v_addc_co_u32_e32 v7, vcc, 0, v5, vcc
	v_add_co_u32_e32 v10, vcc, s0, v4
	s_mov_b32 s0, 0x18208000
	s_nop 0
	v_addc_co_u32_e32 v11, vcc, 0, v5, vcc
	global_load_dword v49, v[12:13], off offset:2048
	global_load_dword v50, v[12:13], off offset:3072
	global_load_dword v51, v[14:15], off offset:-4096
	global_load_dword v52, v[14:15], off
	global_load_dword v53, v[14:15], off offset:1024
	global_load_dword v54, v[14:15], off offset:2048
	global_load_dword v55, v[14:15], off offset:3072
	global_load_dword v56, v[10:11], off offset:-4096
	v_add_co_u32_e32 v12, vcc, s0, v4
	s_mov_b32 s0, 0x18209000
	s_nop 0
	v_addc_co_u32_e32 v13, vcc, 0, v5, vcc
	v_add_co_u32_e32 v14, vcc, s0, v4
	s_mov_b32 s0, 0x1820a000
	s_nop 0
	v_addc_co_u32_e32 v15, vcc, 0, v5, vcc
	global_load_dword v57, v[10:11], off
	global_load_dword v58, v[10:11], off offset:1024
	global_load_dword v59, v[10:11], off offset:2048
	global_load_dword v60, v[10:11], off offset:3072
	global_load_dword v61, v[14:15], off offset:-4096
	global_load_dword v62, v[14:15], off
	global_load_dword v63, v[14:15], off offset:1024
	global_load_dword v64, v[14:15], off offset:2048
	v_add_co_u32_e32 v10, vcc, s0, v4
	s_mov_b32 s0, 0x1820b000
	s_nop 0
	v_addc_co_u32_e32 v11, vcc, 0, v5, vcc
	v_add_co_u32_e32 v16, vcc, s0, v4
	s_mov_b32 s0, 0x1820c000
	s_nop 0
	v_addc_co_u32_e32 v17, vcc, 0, v5, vcc
	global_load_dword v65, v[8:9], off offset:3072
	global_load_dword v66, v[6:7], off offset:1024
	global_load_dword v67, v[6:7], off offset:2048
	global_load_dword v68, v[6:7], off offset:3072
	global_load_dword v69, v[12:13], off offset:1024
	global_load_dword v70, v[12:13], off offset:2048
	global_load_dword v71, v[12:13], off offset:3072
	global_load_dword v72, v[10:11], off offset:1024
	v_add_co_u32_e32 v6, vcc, s0, v4
	s_mov_b32 s0, 0x1820d000
	s_nop 0
	v_addc_co_u32_e32 v7, vcc, 0, v5, vcc
	v_add_co_u32_e32 v20, vcc, s0, v4
	s_mov_b32 s0, 0x1820e000
	s_nop 0
	v_addc_co_u32_e32 v21, vcc, 0, v5, vcc
	v_add_co_u32_e32 v8, vcc, s0, v4
	s_mov_b32 s0, 0x1820f000
	s_nop 0
	v_addc_co_u32_e32 v9, vcc, 0, v5, vcc
	v_add_co_u32_e32 v4, vcc, s0, v4
	s_mov_b32 s0, 0xbfb8aa3b
	global_load_dword v73, v[14:15], off offset:3072
	global_load_dword v74, v[16:17], off offset:-4096
	global_load_dword v42, v[16:17], off
	global_load_dword v41, v[16:17], off offset:1024
	global_load_dword v40, v[16:17], off offset:2048
	global_load_dword v36, v[16:17], off offset:3072
	global_load_dword v34, v[20:21], off offset:-4096
	global_load_dword v25, v[20:21], off
	global_load_dword v75, v[10:11], off offset:2048
	global_load_dword v76, v[10:11], off offset:3072
	global_load_dword v37, v[6:7], off offset:1024
	global_load_dword v33, v[6:7], off offset:2048
	global_load_dword v31, v[6:7], off offset:3072
	global_load_dword v19, v[8:9], off offset:1024
	global_load_dword v16, v[8:9], off offset:2048
	global_load_dword v14, v[8:9], off offset:3072
	v_addc_co_u32_e32 v5, vcc, 0, v5, vcc
	global_load_dword v30, v[20:21], off offset:1024
	global_load_dword v28, v[20:21], off offset:2048
	global_load_dword v26, v[20:21], off offset:3072
	global_load_dword v24, v[4:5], off offset:-4096
	global_load_dword v15, v[4:5], off
	global_load_dword v13, v[4:5], off offset:1024
	global_load_dword v10, v[4:5], off offset:2048
	global_load_dword v9, v[4:5], off offset:3072
	s_ashr_i32 s5, s4, 31
	s_waitcnt vmcnt(62)
; __device__ __forceinline__ void phase_shift_cum(const Args& A, int gtid, int NGT, int gw, int lane) {
;     ...
;         float loc = 0.f;
; #pragma unroll
;         for (int i = 0; i < 64; ++i) { const float z = zv[i] + bf; loc += fminf(z, 0.f) - 0.6931471805599453f * __builtin_amdgcn_logf(1.0f + __builtin_amdgcn_exp2f(-1.4426950408889634f * fabsf(z))); zv[i] = loc; }
	v_add_f32_e32 v0, v3, v0
	v_mul_f32_e64 v6, |v0|, s0
	v_exp_f32_e32 v6, v6
	v_min_f32_e32 v0, 0, v0
	s_waitcnt vmcnt(60)
	v_add_f32_e32 v17, v3, v23
	s_waitcnt vmcnt(55)
	v_add_f32_e32 v5, v3, v38
	v_add_f32_e32 v4, 1.0, v6
	v_mul_f32_e64 v6, |v5|, s0
	v_log_f32_e32 v4, v4
	v_exp_f32_e32 v6, v6
	s_waitcnt vmcnt(53)
	v_add_f32_e32 v8, v3, v43
	v_mul_f32_e64 v11, |v8|, s0
	v_fmac_f32_e32 v0, 0xbf317218, v4
	v_min_f32_e32 v4, 0, v5
	v_add_f32_e32 v5, 1.0, v6
	v_add_f32_e32 v6, v3, v39
	v_mul_f32_e64 v7, |v6|, s0
	v_log_f32_e32 v5, v5
	v_exp_f32_e32 v7, v7
	v_exp_f32_e32 v11, v11
	s_waitcnt vmcnt(52)
	v_add_f32_e32 v21, v3, v44
	v_fmac_f32_e32 v4, 0xbf317218, v5
	v_add_f32_e32 v5, 1.0, v7
	v_log_f32_e32 v7, v5
	v_add_f32_e32 v5, 1.0, v11
	v_log_f32_e32 v11, v5
	v_min_f32_e32 v5, 0, v6
	v_fmac_f32_e32 v5, 0xbf317218, v7
	v_min_f32_e32 v6, 0, v8
	v_add_f32_e32 v7, v3, v18
	v_fmac_f32_e32 v6, 0xbf317218, v11
	v_mul_f32_e64 v8, |v7|, s0
	v_add_f32_e32 v11, v3, v22
	v_exp_f32_e32 v8, v8
	v_mul_f32_e64 v12, |v11|, s0
	v_exp_f32_e32 v12, v12
	v_mul_f32_e64 v18, |v17|, s0
	v_add_f32_e32 v8, 1.0, v8
	v_log_f32_e32 v8, v8
	v_add_f32_e32 v12, 1.0, v12
	v_exp_f32_e32 v18, v18
	v_log_f32_e32 v12, v12
	v_min_f32_e32 v7, 0, v7
	v_fmac_f32_e32 v7, 0xbf317218, v8
	v_min_f32_e32 v8, 0, v11
	v_add_f32_e32 v11, 1.0, v18
	v_add_f32_e32 v18, v3, v27
	v_fmac_f32_e32 v8, 0xbf317218, v12
	v_log_f32_e32 v12, v11
	v_mul_f32_e64 v11, |v18|, s0
	v_exp_f32_e32 v20, v11
	v_min_f32_e32 v11, 0, v17
	v_fmac_f32_e32 v11, 0xbf317218, v12
	v_min_f32_e32 v12, 0, v18
	v_add_f32_e32 v18, v3, v29
	v_add_f32_e32 v17, 1.0, v20
	v_mul_f32_e64 v20, |v18|, s0
	v_log_f32_e32 v17, v17
	v_exp_f32_e32 v20, v20
	v_mul_f32_e64 v22, |v21|, s0
	v_exp_f32_e32 v22, v22
	v_fmac_f32_e32 v12, 0xbf317218, v17
	v_add_f32_e32 v17, 1.0, v20
	v_log_f32_e32 v20, v17
	v_add_f32_e32 v17, 1.0, v22
	v_log_f32_e32 v22, v17
	v_min_f32_e32 v17, 0, v18
	v_fmac_f32_e32 v17, 0xbf317218, v20
	v_min_f32_e32 v18, 0, v21
	s_waitcnt vmcnt(51)
	v_add_f32_e32 v20, v3, v45
	v_fmac_f32_e32 v18, 0xbf317218, v22
	v_mul_f32_e64 v21, |v20|, s0
	s_waitcnt vmcnt(50)
	v_add_f32_e32 v22, v3, v46
	v_exp_f32_e32 v21, v21
	v_mul_f32_e64 v23, |v22|, s0
	v_exp_f32_e32 v23, v23
	v_add_f32_e32 v27, v3, v32
	v_add_f32_e32 v21, 1.0, v21
	v_mul_f32_e64 v29, |v27|, s0
	v_log_f32_e32 v21, v21
	v_add_f32_e32 v23, 1.0, v23
	v_exp_f32_e32 v29, v29
	v_log_f32_e32 v23, v23
	v_min_f32_e32 v20, 0, v20
	v_fmac_f32_e32 v20, 0xbf317218, v21
	v_min_f32_e32 v21, 0, v22
	v_add_f32_e32 v22, 1.0, v29
	v_add_f32_e32 v29, v3, v35
	v_fmac_f32_e32 v21, 0xbf317218, v23
	v_log_f32_e32 v23, v22
	v_mul_f32_e64 v22, |v29|, s0
	v_exp_f32_e32 v32, v22
	v_min_f32_e32 v22, 0, v27
	v_fmac_f32_e32 v22, 0xbf317218, v23
	v_min_f32_e32 v23, 0, v29
	s_waitcnt vmcnt(47)
	v_add_f32_e32 v29, v3, v49
	v_add_f32_e32 v27, 1.0, v32
	v_mul_f32_e64 v32, |v29|, s0
	s_waitcnt vmcnt(46)
	v_add_f32_e32 v35, v3, v50
	v_log_f32_e32 v27, v27
	v_exp_f32_e32 v32, v32
	v_mul_f32_e64 v38, |v35|, s0
	v_exp_f32_e32 v38, v38
	v_fmac_f32_e32 v23, 0xbf317218, v27
	v_add_f32_e32 v27, 1.0, v32
	v_log_f32_e32 v32, v27
	v_add_f32_e32 v27, 1.0, v38
	v_log_f32_e32 v38, v27
	v_min_f32_e32 v27, 0, v29
	v_fmac_f32_e32 v27, 0xbf317218, v32
	v_min_f32_e32 v29, 0, v35
	s_waitcnt vmcnt(45)
	v_add_f32_e32 v32, v3, v51
	v_fmac_f32_e32 v29, 0xbf317218, v38
	v_mul_f32_e64 v35, |v32|, s0
	v_add_f32_e32 v38, v3, v47
	v_exp_f32_e32 v35, v35
	v_mul_f32_e64 v39, |v38|, s0
	v_exp_f32_e32 v39, v39
	v_add_f32_e32 v43, v3, v48
	v_add_f32_e32 v35, 1.0, v35
	v_mul_f32_e64 v44, |v43|, s0
	v_log_f32_e32 v35, v35
	v_add_f32_e32 v39, 1.0, v39
	v_exp_f32_e32 v44, v44
	v_log_f32_e32 v39, v39
	v_min_f32_e32 v32, 0, v32
	v_fmac_f32_e32 v32, 0xbf317218, v35
	v_min_f32_e32 v35, 0, v38
	v_add_f32_e32 v38, 1.0, v44
	s_waitcnt vmcnt(31)
	v_add_f32_e32 v44, v3, v65
	v_fmac_f32_e32 v35, 0xbf317218, v39
	v_log_f32_e32 v39, v38
	v_mul_f32_e64 v38, |v44|, s0
	v_exp_f32_e32 v45, v38
	v_min_f32_e32 v38, 0, v43
	v_fmac_f32_e32 v38, 0xbf317218, v39
	v_min_f32_e32 v39, 0, v44
	v_add_f32_e32 v44, v3, v52
	v_add_f32_e32 v43, 1.0, v45
	v_mul_f32_e64 v45, |v44|, s0
	v_add_f32_e32 v46, v3, v53
	v_log_f32_e32 v43, v43
	v_exp_f32_e32 v45, v45
	v_mul_f32_e64 v47, |v46|, s0
	v_exp_f32_e32 v47, v47
	v_fmac_f32_e32 v39, 0xbf317218, v43
	v_add_f32_e32 v43, 1.0, v45
	v_log_f32_e32 v45, v43
	v_add_f32_e32 v43, 1.0, v47
	v_log_f32_e32 v47, v43
	v_min_f32_e32 v43, 0, v44
	v_fmac_f32_e32 v43, 0xbf317218, v45
	v_min_f32_e32 v44, 0, v46
	v_add_f32_e32 v45, v3, v54
	v_fmac_f32_e32 v44, 0xbf317218, v47
	v_mul_f32_e64 v46, |v45|, s0
	v_add_f32_e32 v47, v3, v55
	v_exp_f32_e32 v46, v46
	v_mul_f32_e64 v48, |v47|, s0
	v_exp_f32_e32 v48, v48
	v_add_f32_e32 v49, v3, v56
	v_add_f32_e32 v46, 1.0, v46
	v_log_f32_e32 v46, v46
	v_add_f32_e32 v48, 1.0, v48
	v_log_f32_e32 v48, v48
	v_mul_f32_e64 v50, |v49|, s0
	v_exp_f32_e32 v50, v50
	v_min_f32_e32 v45, 0, v45
	v_fmac_f32_e32 v45, 0xbf317218, v46
	v_min_f32_e32 v46, 0, v47
	v_fmac_f32_e32 v46, 0xbf317218, v48
	s_waitcnt vmcnt(30)
	v_add_f32_e32 v48, v3, v66
	v_add_f32_e32 v47, 1.0, v50
	v_mul_f32_e64 v50, |v48|, s0
	v_log_f32_e32 v47, v47
	v_exp_f32_e32 v50, v50
	v_min_f32_e32 v49, 0, v49
	s_waitcnt vmcnt(28)
; __device__ __forceinline__ void phase_shift_cum(const Args& A, int gtid, int NGT, int gw, int lane) {
;     ...
;         for (int i = 0; i < 64; ++i) { const float z = zv[i] + bf; loc += fminf(z, 0.f) - 0.6931471805599453f * __builtin_amdgcn_logf(1.0f + __builtin_amdgcn_exp2f(-1.4426950408889634f * fabsf(z))); zv[i] = loc; }
	v_add_f32_e32 v52, v3, v68
	v_fmac_f32_e32 v49, 0xbf317218, v47
	v_min_f32_e32 v47, 0, v48
	v_add_f32_e32 v48, 1.0, v50
	v_add_f32_e32 v50, v3, v67
	v_mul_f32_e64 v51, |v50|, s0
	v_log_f32_e32 v48, v48
	v_exp_f32_e32 v51, v51
	v_mul_f32_e64 v53, |v52|, s0
	v_exp_f32_e32 v53, v53
	v_fmac_f32_e32 v47, 0xbf317218, v48
	v_add_f32_e32 v48, 1.0, v51
	v_log_f32_e32 v48, v48
	v_add_f32_e32 v51, 1.0, v53
	v_log_f32_e32 v51, v51
	v_min_f32_e32 v50, 0, v50
	v_fmac_f32_e32 v50, 0xbf317218, v48
	v_min_f32_e32 v48, 0, v52
	v_fmac_f32_e32 v48, 0xbf317218, v51
	v_add_f32_e32 v51, v3, v57
	v_mul_f32_e64 v52, |v51|, s0
	v_add_f32_e32 v53, v3, v58
	v_exp_f32_e32 v52, v52
	v_mul_f32_e64 v54, |v53|, s0
	v_exp_f32_e32 v54, v54
	v_add_f32_e32 v55, v3, v59
	v_add_f32_e32 v52, 1.0, v52
	v_log_f32_e32 v52, v52
	v_add_f32_e32 v54, 1.0, v54
	v_log_f32_e32 v54, v54
	v_mul_f32_e64 v56, |v55|, s0
	v_exp_f32_e32 v56, v56
	v_min_f32_e32 v51, 0, v51
	v_fmac_f32_e32 v51, 0xbf317218, v52
	v_min_f32_e32 v52, 0, v53
	v_fmac_f32_e32 v52, 0xbf317218, v54
	v_add_f32_e32 v54, v3, v60
	v_add_f32_e32 v53, 1.0, v56
	v_mul_f32_e64 v56, |v54|, s0
	v_log_f32_e32 v53, v53
	v_exp_f32_e32 v56, v56
	v_min_f32_e32 v55, 0, v55
	s_waitcnt vmcnt(27)
	v_add_f32_e32 v58, v3, v69
	v_fmac_f32_e32 v55, 0xbf317218, v53
	v_min_f32_e32 v53, 0, v54
	v_add_f32_e32 v54, 1.0, v56
	v_add_f32_e32 v56, v3, v61
	v_mul_f32_e64 v57, |v56|, s0
	v_log_f32_e32 v54, v54
	v_exp_f32_e32 v57, v57
	v_mul_f32_e64 v59, |v58|, s0
	v_exp_f32_e32 v59, v59
	v_fmac_f32_e32 v53, 0xbf317218, v54
	v_add_f32_e32 v54, 1.0, v57
	v_log_f32_e32 v54, v54
	v_add_f32_e32 v57, 1.0, v59
	v_log_f32_e32 v57, v57
	v_min_f32_e32 v56, 0, v56
	v_fmac_f32_e32 v56, 0xbf317218, v54
	v_min_f32_e32 v54, 0, v58
	v_fmac_f32_e32 v54, 0xbf317218, v57
	s_waitcnt vmcnt(26)
	v_add_f32_e32 v57, v3, v70
	v_mul_f32_e64 v58, |v57|, s0
	s_waitcnt vmcnt(25)
	v_add_f32_e32 v59, v3, v71
	v_exp_f32_e32 v58, v58
	v_mul_f32_e64 v60, |v59|, s0
	v_exp_f32_e32 v60, v60
	v_add_f32_e32 v61, v3, v62
	v_add_f32_e32 v58, 1.0, v58
	v_log_f32_e32 v58, v58
	v_add_f32_e32 v60, 1.0, v60
	v_log_f32_e32 v60, v60
	v_mul_f32_e64 v62, |v61|, s0
	v_exp_f32_e32 v62, v62
	v_min_f32_e32 v57, 0, v57
	v_fmac_f32_e32 v57, 0xbf317218, v58
	v_min_f32_e32 v58, 0, v59
	v_fmac_f32_e32 v58, 0xbf317218, v60
	v_add_f32_e32 v60, v3, v63
	v_add_f32_e32 v59, 1.0, v62
	v_mul_f32_e64 v62, |v60|, s0
	v_log_f32_e32 v59, v59
	v_exp_f32_e32 v62, v62
	v_min_f32_e32 v61, 0, v61
	s_waitcnt vmcnt(15)
	v_add_f32_e32 v67, v3, v75
	v_fmac_f32_e32 v61, 0xbf317218, v59
	v_min_f32_e32 v59, 0, v60
	v_add_f32_e32 v60, 1.0, v62
	v_add_f32_e32 v62, v3, v64
	v_mul_f32_e64 v63, |v62|, s0
	v_add_f32_e32 v64, v3, v73
	v_log_f32_e32 v60, v60
	v_exp_f32_e32 v63, v63
	v_mul_f32_e64 v65, |v64|, s0
	v_exp_f32_e32 v65, v65
	v_fmac_f32_e32 v59, 0xbf317218, v60
	v_add_f32_e32 v60, 1.0, v63
	v_log_f32_e32 v60, v60
	v_add_f32_e32 v63, 1.0, v65
	v_log_f32_e32 v63, v63
	v_min_f32_e32 v62, 0, v62
	v_fmac_f32_e32 v62, 0xbf317218, v60
	v_min_f32_e32 v60, 0, v64
	v_fmac_f32_e32 v60, 0xbf317218, v63
	v_add_f32_e32 v63, v3, v74
	v_mul_f32_e64 v64, |v63|, s0
	v_add_f32_e32 v65, v3, v72
	v_exp_f32_e32 v64, v64
	v_mul_f32_e64 v66, |v65|, s0
	v_exp_f32_e32 v66, v66
	v_mul_f32_e64 v68, |v67|, s0
	v_add_f32_e32 v64, 1.0, v64
	v_log_f32_e32 v64, v64
	v_add_f32_e32 v66, 1.0, v66
	v_log_f32_e32 v66, v66
	v_exp_f32_e32 v68, v68
	v_min_f32_e32 v63, 0, v63
	v_fmac_f32_e32 v63, 0xbf317218, v64
	v_min_f32_e32 v64, 0, v65
	v_fmac_f32_e32 v64, 0xbf317218, v66
	s_waitcnt vmcnt(14)
	v_add_f32_e32 v66, v3, v76
	v_add_f32_e32 v65, 1.0, v68
	v_mul_f32_e64 v68, |v66|, s0
	v_log_f32_e32 v65, v65
	v_exp_f32_e32 v68, v68
	v_min_f32_e32 v67, 0, v67
	v_add_f32_e32 v42, v3, v42
	v_fmac_f32_e32 v67, 0xbf317218, v65
	v_min_f32_e32 v65, 0, v66
	v_add_f32_e32 v66, 1.0, v68
	v_mul_f32_e64 v68, |v42|, s0
	v_log_f32_e32 v66, v66
	v_exp_f32_e32 v68, v68
	v_add_f32_e32 v41, v3, v41
	v_mul_f32_e64 v69, |v41|, s0
	v_exp_f32_e32 v69, v69
	v_fmac_f32_e32 v65, 0xbf317218, v66
	v_add_f32_e32 v66, 1.0, v68
	v_log_f32_e32 v66, v66
	v_add_f32_e32 v68, 1.0, v69
	v_min_f32_e32 v69, 0, v42
	v_add_f32_e32 v40, v3, v40
	v_add_f32_e32 v36, v3, v36
	v_fmac_f32_e32 v69, 0xbf317218, v66
	v_min_f32_e32 v66, 0, v41
	v_mul_f32_e64 v41, |v40|, s0
	v_mul_f32_e64 v42, |v36|, s0
	v_log_f32_e32 v68, v68
	v_exp_f32_e32 v41, v41
	v_exp_f32_e32 v42, v42
	v_add_f32_e32 v34, v3, v34
	v_fmac_f32_e32 v66, 0xbf317218, v68
	v_min_f32_e32 v68, 0, v40
	v_add_f32_e32 v40, 1.0, v41
	v_add_f32_e32 v41, 1.0, v42
	v_mul_f32_e64 v42, |v34|, s0
	v_exp_f32_e32 v42, v42
	v_min_f32_e32 v70, 0, v36
	v_log_f32_e32 v40, v40
	s_waitcnt vmcnt(13)
	v_add_f32_e32 v37, v3, v37
	v_add_f32_e32 v36, 1.0, v42
	v_log_f32_e32 v36, v36
	v_min_f32_e32 v71, 0, v34
	s_waitcnt vmcnt(12)
	v_add_f32_e32 v33, v3, v33
	s_waitcnt vmcnt(11)
	v_add_f32_e32 v31, v3, v31
	v_add_f32_e32 v25, v3, v25
	s_waitcnt vmcnt(7)
	v_add_f32_e32 v30, v3, v30
	v_fmac_f32_e32 v68, 0xbf317218, v40
	v_mul_f32_e64 v40, |v37|, s0
	v_fmac_f32_e32 v71, 0xbf317218, v36
	v_min_f32_e32 v72, 0, v37
	v_mul_f32_e64 v36, |v33|, s0
	v_mul_f32_e64 v37, |v31|, s0
	v_min_f32_e32 v73, 0, v33
	v_min_f32_e32 v74, 0, v31
	v_mul_f32_e64 v31, |v25|, s0
	v_mul_f32_e64 v33, |v30|, s0
	v_exp_f32_e32 v31, v31
	v_exp_f32_e32 v33, v33
	s_waitcnt vmcnt(6)
	v_add_f32_e32 v28, v3, v28
	s_waitcnt vmcnt(5)
	v_add_f32_e32 v26, v3, v26
	s_waitcnt vmcnt(4)
; __device__ __forceinline__ void phase_shift_cum(const Args& A, int gtid, int NGT, int gw, int lane) {
;     ...
;         for (int i = 0; i < 64; ++i) { const float z = zv[i] + bf; loc += fminf(z, 0.f) - 0.6931471805599453f * __builtin_amdgcn_logf(1.0f + __builtin_amdgcn_exp2f(-1.4426950408889634f * fabsf(z))); zv[i] = loc; }
;         float incl = loc;
; #pragma unroll
;         for (int o = 1; o < 64; o <<= 1) { const float n = __shfl_up(incl, o); if (lane >= o) incl += n; }
	v_add_f32_e32 v24, v3, v24
	v_add_f32_e32 v19, v3, v19
	v_add_f32_e32 v16, v3, v16
	v_add_f32_e32 v14, v3, v14
	v_min_f32_e32 v75, 0, v25
	v_add_f32_e32 v25, 1.0, v31
	v_add_f32_e32 v31, 1.0, v33
	v_mul_f32_e64 v33, |v28|, s0
	v_min_f32_e32 v76, 0, v30
	v_mul_f32_e64 v30, |v26|, s0
	v_min_f32_e32 v77, 0, v28
	v_min_f32_e32 v78, 0, v26
	v_mul_f32_e64 v26, |v24|, s0
	v_mul_f32_e64 v28, |v19|, s0
	v_min_f32_e32 v79, 0, v24
	v_min_f32_e32 v80, 0, v19
	v_mul_f32_e64 v19, |v16|, s0
	v_mul_f32_e64 v24, |v14|, s0
	v_exp_f32_e32 v19, v19
	v_exp_f32_e32 v24, v24
	s_waitcnt vmcnt(3)
	v_add_f32_e32 v15, v3, v15
	v_min_f32_e32 v81, 0, v16
	v_add_f32_e32 v16, 1.0, v19
	v_add_f32_e32 v19, 1.0, v24
	v_mul_f32_e64 v24, |v15|, s0
	v_log_f32_e32 v16, v16
	v_exp_f32_e32 v24, v24
	s_waitcnt vmcnt(2)
	v_add_f32_e32 v13, v3, v13
	s_waitcnt vmcnt(1)
	v_add_f32_e32 v10, v3, v10
	s_waitcnt vmcnt(0)
	v_add_f32_e32 v3, v3, v9
	v_mul_f32_e64 v9, |v3|, s0
	v_fmac_f32_e32 v81, 0xbf317218, v16
	v_min_f32_e32 v82, 0, v14
	v_add_f32_e32 v14, 1.0, v24
	v_mul_f32_e64 v16, |v13|, s0
	v_exp_f32_e32 v9, v9
	v_log_f32_e32 v14, v14
	v_exp_f32_e32 v16, v16
	v_min_f32_e32 v83, 0, v15
	v_add_f32_e32 v9, 1.0, v9
	v_fmac_f32_e32 v83, 0xbf317218, v14
	v_min_f32_e32 v84, 0, v13
	v_add_f32_e32 v13, 1.0, v16
	v_mul_f32_e64 v14, |v10|, s0
	v_log_f32_e32 v9, v9
	v_log_f32_e32 v13, v13
	v_exp_f32_e32 v14, v14
	v_min_f32_e32 v3, 0, v3
	v_fmac_f32_e32 v3, 0xbf317218, v9
	v_mbcnt_lo_u32_b32 v9, -1, 0
	v_fmac_f32_e32 v84, 0xbf317218, v13
	v_add_f32_e32 v13, 1.0, v14
	v_mbcnt_hi_u32_b32 v86, -1, v9
	v_add_f32_e32 v14, 0, v0
	v_and_b32_e32 v87, 64, v86
	v_add_u32_e32 v9, -1, v86
	v_add_f32_e32 v15, v14, v4
	v_log_f32_e32 v25, v25
	v_exp_f32_e32 v33, v33
	v_cmp_lt_i32_e32 vcc, v9, v87
	v_add_f32_e32 v4, v15, v5
	v_add_f32_e32 v5, v4, v6
	v_cndmask_b32_e32 v9, v9, v86, vcc
	v_lshlrev_b32_e32 v88, 2, v9
	v_add_u32_e32 v9, -2, v86
	v_add_f32_e32 v6, v5, v7
	v_cmp_lt_i32_e32 vcc, v9, v87
	v_add_f32_e32 v7, v6, v8
	v_fmac_f32_e32 v75, 0xbf317218, v25
	v_add_f32_e32 v25, 1.0, v33
	v_cndmask_b32_e32 v9, v9, v86, vcc
	v_add_f32_e32 v8, v7, v11
	v_log_f32_e32 v25, v25
	v_exp_f32_e32 v30, v30
	v_log_f32_e32 v13, v13
	v_lshlrev_b32_e32 v89, 2, v9
	v_add_f32_e32 v9, v8, v12
	v_min_f32_e32 v85, 0, v10
	v_add_f32_e32 v10, v9, v17
	v_add_f32_e32 v11, v10, v18
	v_add_f32_e32 v12, v11, v20
	v_fmac_f32_e32 v77, 0xbf317218, v25
	v_add_f32_e32 v25, 1.0, v30
	v_log_f32_e32 v19, v19
	v_fmac_f32_e32 v85, 0xbf317218, v13
	v_add_f32_e32 v13, v12, v21
	v_log_f32_e32 v25, v25
	v_exp_f32_e32 v26, v26
	v_add_f32_e32 v16, v13, v22
	v_exp_f32_e32 v28, v28
	v_add_f32_e32 v17, v16, v23
	v_add_f32_e32 v18, v17, v27
	v_fmac_f32_e32 v82, 0xbf317218, v19
	v_add_f32_e32 v19, v18, v29
	v_exp_f32_e32 v40, v40
	v_fmac_f32_e32 v78, 0xbf317218, v25
	v_add_f32_e32 v25, 1.0, v26
	v_add_f32_e32 v20, v19, v32
	v_log_f32_e32 v25, v25
	v_add_f32_e32 v26, 1.0, v28
	v_add_f32_e32 v21, v20, v35
	v_log_f32_e32 v26, v26
	v_add_f32_e32 v22, v21, v38
	v_add_f32_e32 v23, v22, v39
	v_add_f32_e32 v34, 1.0, v40
	v_add_f32_e32 v24, v23, v43
	v_log_f32_e32 v34, v34
	v_exp_f32_e32 v36, v36
	v_fmac_f32_e32 v79, 0xbf317218, v25
	v_add_f32_e32 v25, v24, v44
	v_fmac_f32_e32 v80, 0xbf317218, v26
	v_add_f32_e32 v26, v25, v45
	v_exp_f32_e32 v37, v37
	v_log_f32_e32 v31, v31
	v_add_f32_e32 v27, v26, v46
	v_add_f32_e32 v28, v27, v49
	v_fmac_f32_e32 v72, 0xbf317218, v34
	v_add_f32_e32 v34, 1.0, v36
	v_add_f32_e32 v29, v28, v47
	v_log_f32_e32 v34, v34
	v_add_f32_e32 v30, v29, v50
	v_add_f32_e32 v36, 1.0, v37
	v_fmac_f32_e32 v76, 0xbf317218, v31
	v_add_f32_e32 v31, v30, v48
	v_log_f32_e32 v36, v36
	v_add_f32_e32 v32, v31, v51
	v_add_f32_e32 v33, v32, v52
	v_fmac_f32_e32 v73, 0xbf317218, v34
	v_add_f32_e32 v34, v33, v55
	v_add_f32_e32 v35, v34, v53
	v_fmac_f32_e32 v74, 0xbf317218, v36
	v_add_f32_e32 v36, v35, v56
	v_log_f32_e32 v41, v41
	v_add_f32_e32 v37, v36, v54
	v_add_f32_e32 v38, v37, v57
	v_add_f32_e32 v39, v38, v58
	v_add_f32_e32 v40, v39, v61
	v_fmac_f32_e32 v70, 0xbf317218, v41
	v_add_f32_e32 v41, v40, v59
	v_add_f32_e32 v42, v41, v62
	v_add_f32_e32 v43, v42, v60
	v_add_f32_e32 v44, v43, v63
	v_add_f32_e32 v45, v44, v64
	v_add_f32_e32 v46, v45, v67
	v_add_f32_e32 v47, v46, v65
	v_add_f32_e32 v48, v47, v69
	v_add_f32_e32 v49, v48, v66
	v_add_f32_e32 v50, v49, v68
	v_add_f32_e32 v51, v50, v70
	v_add_f32_e32 v52, v51, v71
	v_add_f32_e32 v53, v52, v72
	v_add_f32_e32 v54, v53, v73
	v_add_f32_e32 v55, v54, v74
	v_add_f32_e32 v56, v55, v75
	v_add_f32_e32 v57, v56, v76
	v_add_f32_e32 v58, v57, v77
	v_add_f32_e32 v59, v58, v78
	v_add_f32_e32 v60, v59, v79
	v_add_f32_e32 v61, v60, v80
	v_add_f32_e32 v62, v61, v81
	v_add_f32_e32 v63, v62, v82
	v_add_f32_e32 v64, v63, v83
	v_add_f32_e32 v65, v64, v84
	v_add_f32_e32 v66, v65, v85
	v_add_f32_e32 v67, v66, v3
	ds_bpermute_b32 v0, v88, v67
	v_add_u32_e32 v90, -4, v86
	v_cmp_lt_i32_e32 vcc, v90, v87
	v_add_u32_e32 v68, -8, v86
	v_add_u32_e32 v70, -16, v86
	v_cndmask_b32_e32 v3, v90, v86, vcc
	s_waitcnt lgkmcnt(0)
; __device__ __forceinline__ void phase_shift_cum(const Args& A, int gtid, int NGT, int gw, int lane) {
;     ...
;         for (int o = 1; o < 64; o <<= 1) { const float n = __shfl_up(incl, o); if (lane >= o) incl += n; }
;         const float off = incl - loc; float* dst = CUM + (size_t)gw * T + lane * 64;
; #pragma unroll
;         for (int i = 0; i < 64; i += 4) *(f32x4*)(dst + i) = (f32x4){zv[i] + off, zv[i + 1] + off, zv[i + 2] + off, zv[i + 3] + off};
	v_add_f32_e32 v0, v67, v0
	v_cmp_eq_u32_e32 vcc, 0, v2
	v_lshlrev_b32_e32 v3, 2, v3
	s_lshl_b64 s[0:1], s[4:5], 14
	v_cndmask_b32_e32 v0, v0, v67, vcc
	ds_bpermute_b32 v69, v89, v0
	v_cmp_lt_i32_e32 vcc, v68, v87
	s_add_u32 s0, s34, s0
	s_addc_u32 s1, s35, s1
	v_cndmask_b32_e32 v68, v68, v86, vcc
	s_waitcnt lgkmcnt(0)
	v_add_f32_e32 v69, v0, v69
	v_cmp_gt_u32_e32 vcc, 2, v2
	v_lshlrev_b32_e32 v68, 2, v68
	s_nop 0
	v_cndmask_b32_e32 v0, v69, v0, vcc
	ds_bpermute_b32 v3, v3, v0
	v_cmp_lt_i32_e32 vcc, v70, v87
	s_waitcnt lgkmcnt(0)
	v_add_f32_e32 v3, v0, v3
	v_cndmask_b32_e32 v69, v70, v86, vcc
	v_cmp_gt_u32_e32 vcc, 4, v2
	v_subrev_u32_e32 v70, 32, v86
	v_lshlrev_b32_e32 v69, 2, v69
	v_cndmask_b32_e32 v0, v3, v0, vcc
	ds_bpermute_b32 v3, v68, v0
	v_cmp_lt_i32_e32 vcc, v70, v87
	s_waitcnt lgkmcnt(0)
	v_add_f32_e32 v3, v0, v3
	v_cndmask_b32_e32 v68, v70, v86, vcc
	v_cmp_gt_u32_e32 vcc, 8, v2
	v_lshlrev_b32_e32 v68, 2, v68
	s_nop 0
	v_cndmask_b32_e32 v3, v3, v0, vcc
	ds_bpermute_b32 v69, v69, v3
	v_cmp_gt_u32_e32 vcc, 16, v2
	v_lshlrev_b32_e32 v0, 8, v2
	s_waitcnt lgkmcnt(0)
	v_add_f32_e32 v69, v3, v69
	v_cndmask_b32_e32 v3, v69, v3, vcc
	ds_bpermute_b32 v72, v68, v3
	v_lshl_add_u64 v[68:69], s[0:1], 0, v[0:1]
	v_cmp_gt_u32_e32 vcc, 32, v2
	s_mov_b64 s[0:1], 0x28800000
	v_lshl_add_u64 v[70:71], v[68:69], 0, s[0:1]
	s_waitcnt lgkmcnt(0)
	v_add_f32_e32 v0, v3, v72
	v_cndmask_b32_e32 v0, v0, v3, vcc
	v_sub_f32_e32 v72, v0, v67
	s_mov_b32 s0, 0x28800000
	v_pk_add_f32 v[2:3], v[4:5], v[72:73] op_sel_hi:[1,0]
	v_add_co_u32_e32 v4, vcc, s0, v68
	v_pk_add_f32 v[0:1], v[14:15], v[72:73] op_sel_hi:[1,0]
	s_nop 0
	v_addc_co_u32_e32 v5, vcc, 0, v69, vcc
	global_store_dwordx4 v[4:5], v[0:3], off
	s_nop 1
	v_pk_add_f32 v[2:3], v[8:9], v[72:73] op_sel_hi:[1,0]
	v_pk_add_f32 v[0:1], v[6:7], v[72:73] op_sel_hi:[1,0]
	global_store_dwordx4 v[70:71], v[0:3], off offset:16
	s_nop 1
	v_pk_add_f32 v[2:3], v[12:13], v[72:73] op_sel_hi:[1,0]
	v_pk_add_f32 v[0:1], v[10:11], v[72:73] op_sel_hi:[1,0]
	global_store_dwordx4 v[70:71], v[0:3], off offset:32
	s_nop 1
	v_pk_add_f32 v[2:3], v[18:19], v[72:73] op_sel_hi:[1,0]
	v_pk_add_f32 v[0:1], v[16:17], v[72:73] op_sel_hi:[1,0]
	global_store_dwordx4 v[70:71], v[0:3], off offset:48
	s_nop 1
	v_pk_add_f32 v[2:3], v[22:23], v[72:73] op_sel_hi:[1,0]
	v_pk_add_f32 v[0:1], v[20:21], v[72:73] op_sel_hi:[1,0]
	global_store_dwordx4 v[70:71], v[0:3], off offset:64
	s_nop 1
	v_pk_add_f32 v[2:3], v[26:27], v[72:73] op_sel_hi:[1,0]
	v_pk_add_f32 v[0:1], v[24:25], v[72:73] op_sel_hi:[1,0]
	global_store_dwordx4 v[70:71], v[0:3], off offset:80
	s_nop 1
	v_pk_add_f32 v[2:3], v[30:31], v[72:73] op_sel_hi:[1,0]
	v_pk_add_f32 v[0:1], v[28:29], v[72:73] op_sel_hi:[1,0]
	global_store_dwordx4 v[70:71], v[0:3], off offset:96
	s_nop 1
	v_pk_add_f32 v[2:3], v[34:35], v[72:73] op_sel_hi:[1,0]
	v_pk_add_f32 v[0:1], v[32:33], v[72:73] op_sel_hi:[1,0]
	global_store_dwordx4 v[70:71], v[0:3], off offset:112
	s_nop 1
	v_pk_add_f32 v[2:3], v[38:39], v[72:73] op_sel_hi:[1,0]
	v_pk_add_f32 v[0:1], v[36:37], v[72:73] op_sel_hi:[1,0]
	global_store_dwordx4 v[70:71], v[0:3], off offset:128
	s_nop 1
	v_pk_add_f32 v[2:3], v[42:43], v[72:73] op_sel_hi:[1,0]
	v_pk_add_f32 v[0:1], v[40:41], v[72:73] op_sel_hi:[1,0]
	global_store_dwordx4 v[70:71], v[0:3], off offset:144
	s_nop 1
	v_pk_add_f32 v[2:3], v[46:47], v[72:73] op_sel_hi:[1,0]
	v_pk_add_f32 v[0:1], v[44:45], v[72:73] op_sel_hi:[1,0]
	global_store_dwordx4 v[70:71], v[0:3], off offset:160
	s_nop 1
	v_pk_add_f32 v[2:3], v[50:51], v[72:73] op_sel_hi:[1,0]
	v_pk_add_f32 v[0:1], v[48:49], v[72:73] op_sel_hi:[1,0]
	global_store_dwordx4 v[70:71], v[0:3], off offset:176
	s_nop 1
	v_pk_add_f32 v[2:3], v[54:55], v[72:73] op_sel_hi:[1,0]
	v_pk_add_f32 v[0:1], v[52:53], v[72:73] op_sel_hi:[1,0]
	global_store_dwordx4 v[70:71], v[0:3], off offset:192
	s_nop 1
	v_pk_add_f32 v[2:3], v[58:59], v[72:73] op_sel_hi:[1,0]
	v_pk_add_f32 v[0:1], v[56:57], v[72:73] op_sel_hi:[1,0]
	global_store_dwordx4 v[70:71], v[0:3], off offset:208
	s_nop 1
	v_pk_add_f32 v[2:3], v[62:63], v[72:73] op_sel_hi:[1,0]
	v_pk_add_f32 v[0:1], v[60:61], v[72:73] op_sel_hi:[1,0]
	global_store_dwordx4 v[70:71], v[0:3], off offset:224
	s_nop 1
	v_pk_add_f32 v[2:3], v[66:67], v[72:73] op_sel_hi:[1,0]
	v_pk_add_f32 v[0:1], v[64:65], v[72:73] op_sel_hi:[1,0]
	global_store_dwordx4 v[70:71], v[0:3], off offset:240
.Lcm_done:
	s_mov_b64 s[4:5], s[88:89]
	s_mov_b64 s[6:7], s[90:91]
	s_mov_b64 s[22:23], s[92:93]
